# one static s_setprio 1 for waves 4-7 at mixer-phase entry (attention/conv phases run two waves per SIMD)
# speedup vs baseline: 1.0041x; 1.0041x over previous
; #define LAS __attribute__((address_space(3)))
; #define CAS __attribute__((address_space(4)))
; __device__ __forceinline__ int kvperm(int kv) { return (kv & 0x33) | (((kv >> 2) & 1) << 3) | (((kv >> 3) & 1) << 2); }
; __device__ __forceinline__ void attnA_unit(LAS unsigned char* lds, const bf16_t* PROJ, const float* CUM, bf16_t* YCAT, int bg, int bl, int h, int qb, int tid, int wave, int lane) {
;     const int r32 = lane & 31, hi = lane >> 5, NS = 2 * (qb + 1), q0w = 256 * qb + 32 * wave, qpos = q0w + r32;
;     const size_t prow = (size_t)bl * SEQ, grow = (size_t)bg * SEQ;
;     bf16x8 qr[4];
;     { const bf16_t* qp = PROJ + (prow + qpos) * NPROJ + 64 * h + 8 * hi;
; #pragma unroll
;       for (int d0 = 0; d0 < 4; ++d0) qr[d0] = *(const bf16x8*)(qp + 16 * d0); }
;     const float cq = CUM[(grow + qpos) * 4 + h];
;     const int lrow = tid >> 3, lch = tid & 7;
;     const bf16_t* kg = PROJ + (prow + lrow) * NPROJ + 256 + 64 * h + 8 * lch;
;     const bf16_t* vg = PROJ + (prow + 2 * lane) * NPROJ + 512 + 64 * h + 8 * wave;
;     const float* cgp = CUM + (grow + (tid & 127)) * 4 + h;
;     const int kst = A_K + lrow * KROW + lch * 16;
;     const int vpos = 64 * ((2 * lane) >> 6) + kvperm((2 * lane) & 63), vst = A_VT + (8 * wave) * AVS + vpos * 2;
;     u32x4 k0, k1, va, vb; float creg = 0.f;
; __device__ __forceinline__ void mixer_phase(const CAS Args* a, int L, int half, LAS unsigned char* lds, int bid, int tid, int wave, int lane) {
;     const bf16_t* PROJ = (const bf16_t*)(a->ws + WS_PROJ); bf16_t* YCAT = (bf16_t*)(a->ws + WS_YCAT); const float* CUM = (const float*)(a->ws + WS_CUM);
;     const int G = gridDim.x, B0 = 16 * half;
;     for (int u = bid; u < 256; u += G) {
;         const int bl = u >> 4, h = (u >> 2) & 3, pr = u & 3;
;         attnA_unit(lds, PROJ, CUM, YCAT, B0 + bl, bl, h, 7 - pr, tid, wave, lane);
;         attnA_unit(lds, PROJ, CUM, YCAT, B0 + bl, bl, h, pr, tid, wave, lane);
;     }
.LBB0_310:
	s_and_b64 vcc, exec, s[10:11]
	s_cbranch_vccz .LBB0_464
	v_readfirstlane_b32 s98, v228
	s_nop 3
	s_cmp_lt_u32 s98, 0x100
	s_cbranch_scc1 .Lmx_noprio
	s_setprio 1
.Lmx_noprio:
	v_mov_b32_e32 v146, v228
	s_cmp_lg_u32 s0, 8
	s_mov_b32 s42, s2
	v_readfirstlane_b32 s44, v146
	s_cselect_b64 s[96:97], -1, 0
	s_ashr_i32 s39, s44, 6
	s_load_dword s38, s[90:91], 0x0
	s_cmp_eq_u32 s0, 8
	s_cselect_b64 s[76:77], -1, 0
	v_and_b32_e32 v147, 63, v146
	s_and_b64 s[6:7], s[76:77], exec
	v_and_b32_e32 v109, 31, v146
	v_lshrrev_b32_e32 v0, 5, v147
	s_cselect_b32 s43, 16, 0
	s_cmpk_gt_i32 s42, 0xff
	v_ashrrev_i32_e32 v100, 3, v146
	v_and_b32_e32 v106, 0x7f, v146
	v_and_b32_e32 v99, 4, v146
	v_lshlrev_b32_e32 v98, 2, v146
	v_lshlrev_b32_e32 v104, 3, v0
	v_lshlrev_b32_e32 v102, 2, v0
	v_mul_u32_u24_e32 v107, 0x90, v109
	v_lshlrev_b32_e32 v103, 4, v0
	s_cbranch_scc1 .LBB0_368
	s_add_u32 s8, s26, 0x3a100000
	s_addc_u32 s9, s27, 0
	v_lshlrev_b32_e32 v108, 1, v147
	s_lshl_b32 s10, s39, 3
	v_lshlrev_b32_e32 v4, 2, v147
	v_and_b32_e32 v2, 7, v146
	s_ashr_i32 s11, s10, 31
	v_and_b32_e32 v3, 64, v108
	v_and_b32_e32 v4, 8, v4
	v_and_or_b32 v5, v108, 50, v99
	v_lshlrev_b32_e32 v0, 3, v2
	v_lshlrev_b32_e32 v2, 4, v2
	v_or3_b32 v3, v5, v4, v3
	s_mul_i32 s1, s39, 0x880
	s_waitcnt lgkmcnt(0)
	s_movk_i32 s3, 0x90
	s_lshl_b64 s[12:13], s[10:11], 1
	v_mad_u64_u32 v[110:111], s[6:7], v100, s3, v[2:3]
	v_lshl_add_u32 v105, v3, 1, s1
	v_mov_b32_e32 v3, 0x3a100000
	v_mov_b64_e32 v[4:5], s[12:13]
	s_movk_i32 s1, 0x6c00
	v_mad_i64_i32 v[116:117], s[12:13], v100, s50, 0
	s_lshl_b32 s45, s39, 5
	v_ashrrev_i32_e32 v101, 31, v100
	v_cmp_gt_i32_e64 s[6:7], s5, v146
	v_mul_u32_u24_e32 v111, 0x110, v109
	v_lshl_or_b32 v112, v106, 4, v3
	v_mov_b32_e32 v113, v1
	v_mad_u64_u32 v[114:115], s[12:13], v147, s1, v[4:5]
	v_or_b32_e32 v116, v116, v2
	v_lshlrev_b32_e32 v118, 1, v104
	v_lshlrev_b32_e32 v120, 1, v0
	v_lshlrev_b32_e32 v122, 1, v102
	s_mov_b32 s46, s42
	s_mov_b32 s47, s42
	s_branch .LBB0_314
